# K-rotation of the MLP-up GEMM: tile sharers start their K loop at different K offsets (k0=((rank&7)+(rank>>3))&3 tile pairs) so L2 serves the later sharers
# baseline (speedup 1.0000x reference)
; template <class Epi, class Sched, bool ALIGN_EPI = false, bool SP2 = false>
; __device__ __forceinline__ void gemm_phase(PG8_LAS unsigned char* lds, const Gemm g, const Sched& S, const Epi& E, const int tid) {
;     const int wid = __builtin_amdgcn_readfirstlane(tid >> 6), lane = tid & 63, wr = wid >> 2, wc = wid & 3, fr = lane & 15, fq = lane >> 4;
;     const int K = g.K, nt = K / BK;
;     unsigned voffA[2], voffB[2];
; #pragma unroll
;     for (int i = 0; i < 2; ++i) { int R, C; stage_rc(tid * 16 + i * 8192, R, C); const int Rb = Epi::PERM ? (2 * (R & ~31) + perm32(R & 31)) : R;
;         voffA[i] = (unsigned)(R * K + C) * 2u; voffB[i] = (unsigned)(Rb * K + C) * 2u; }
;     const size_t kstep = (size_t)(BK * 2);
;     const size_t hstep = (size_t)HALF * K * 2;
;     const size_t tstep = 2 * hstep;
;     const size_t hstepB = Epi::PERM ? (size_t)32 * K * 2 : hstep;
;     const unsigned ldsw = (unsigned)wid * 1024u;
;     const int aoff = lds_byte(wr * 64 + fr, fq * 8), boff = lds_byte(wc * 32 + fr, fq * 8);
;     ...
;     Unit cur, nxt; int ui = 0;
;     if (!S.next(0, cur)) return;
;     f32x4 acc[2][2][4][2];
;     u32x4 iw_[Epi::HAS_INIT ? 16 : 1];
;     if constexpr (Epi::HAS_INIT) E.init_issue(iw_, cur, wr, wc, fr, fq);
;     else {
; #pragma unroll
;     for (int a = 0; a < 2; ++a)
; #pragma unroll
;         for (int b = 0; b < 2; ++b)
; #pragma unroll
;             for (int m = 0; m < 4; ++m)
; #pragma unroll
;                 for (int n = 0; n < 2; ++n) acc[a][b][m][n] = (f32x4){0.f, 0.f, 0.f, 0.f};
;     }
;     bf16x8 At[4][2], B0[2][2], B1[2][2];
;     const char* cA = (const char*)g.A + (size_t)cur.pm * tstep; const char* cB = (const char*)g.Bt + (size_t)cur.pn * tstep;
;     S.a_ready(cur);
;     if constexpr (SP2) {
;         PG8_STAGE(PG8_SB(0, 0), cB, voffB); PG8_STAGE(PG8_SB(0, 1), cB + hstepB, voffB); PG8_STAGE(PG8_SA(0, 0), cA, voffA); PG8_STAGE(PG8_SA(0, 1), cA + hstep, voffA);
;         if (wr == 1) PG8_BAR;
;         PG8_WAIT_V(2); PG8_BAR;
;         PG8_STAGE(PG8_SB(1, 0), cB + kstep, voffB); PG8_STAGE(PG8_SA(1, 0), cA + kstep, voffA); PG8_STAGE(PG8_SB(1, 1), cB + hstepB + kstep, voffB);
;         PG8_WAIT_V(6); PG8_BAR;
;     } else {
;         PG8_STAGE(PG8_SB(0, 0), cB, voffB); PG8_STAGE(PG8_SA(0, 0), cA, voffA); PG8_STAGE(PG8_SB(0, 1), cB + hstepB, voffB); PG8_STAGE(PG8_SA(0, 1), cA + hstep, voffA);
;         if (wr == 1) PG8_BAR;
.LBB0_1371:
	s_or_b64 exec, exec, s[0:1]
	v_ashrrev_i32_e32 v3, 31, v152
	v_lshrrev_b32_e32 v3, 26, v3
	v_add_u32_e32 v3, v152, v3
	v_ashrrev_i32_e32 v12, 6, v3
	v_bfe_i32 v3, v152, 27, 1
	v_lshlrev_b32_e32 v4, 4, v152
	v_lshrrev_b32_e32 v3, 22, v3
	v_add_u32_e32 v3, v4, v3
	v_and_b32_e32 v3, 0xfffffc00, v3
	v_sub_u32_e32 v3, v4, v3
	v_lshrrev_b32_e32 v5, 4, v3
	s_lshl_b64 s[0:1], s[6:7], 23
	v_bitop3_b32 v3, v5, v3, 32 bitop3:0x6c
	s_add_u32 s6, s4, s0
	v_ashrrev_i32_e32 v6, 31, v3
	s_addc_u32 s7, s5, s1
	v_lshrrev_b32_e32 v6, 26, v6
	s_add_u32 s10, s6, 0x2100000
	v_add_u32_e32 v6, v3, v6
	s_addc_u32 s11, s7, 0
	v_lshlrev_b32_e32 v5, 3, v12
	v_ashrrev_i32_e32 v13, 6, v6
	v_and_b32_e32 v6, 0xc0, v6
	s_add_u32 s6, s4, 0xc300000
	v_and_b32_e32 v5, -16, v5
	v_sub_u32_e32 v3, v3, v6
	s_addc_u32 s7, s5, 0
	v_add_u32_e32 v133, v13, v5
	v_ashrrev_i16_sdwa v3, v205, sext(v3) dst_sel:DWORD dst_unused:UNUSED_PAD src0_sel:DWORD src1_sel:BYTE_0
	s_add_u32 s4, s4, 0x17100000
	v_lshlrev_b32_e32 v5, 5, v12
	v_bfe_i32 v14, v3, 0, 16
	v_lshrrev_b32_e32 v3, 2, v133
	s_addc_u32 s5, s5, 0
	v_and_b32_e32 v5, 32, v5
	v_and_b32_e32 v154, 4, v3
	v_lshrrev_b32_e32 v3, 1, v152
	v_readfirstlane_b32 s14, v152
	v_add_u32_e32 v132, v5, v14
	v_lshlrev_b32_e32 v156, 1, v133
	v_and_b32_e32 v155, 3, v13
	v_and_b32_e32 v153, 15, v152
	s_cmpk_gt_i32 s40, 0x7f
	v_and_b32_e32 v3, 24, v3
	s_waitcnt lgkmcnt(0)
	s_barrier
	s_cbranch_scc1 .LBB0_1387
	v_add_u32_e32 v4, 0x2000, v4
	v_ashrrev_i32_e32 v5, 31, v4
	v_lshrrev_b32_e32 v5, 22, v5
	v_add_u32_e32 v5, v4, v5
	v_ashrrev_i32_e32 v15, 10, v5
	v_mul_i32_i24_e32 v5, 0x400, v15
	v_sub_u32_e32 v4, v4, v5
	v_lshrrev_b32_e32 v5, 4, v4
	v_bitop3_b32 v4, v5, v4, 32 bitop3:0x6c
	v_ashrrev_i32_e32 v5, 31, v4
	v_lshrrev_b32_e32 v5, 26, v5
	v_add_u32_e32 v5, v4, v5
	v_lshlrev_b32_e32 v6, 3, v15
	v_ashrrev_i32_e32 v16, 6, v5
	v_and_b32_e32 v6, -16, v6
	s_lshr_b32 s12, s40, 29
	v_add_u32_e32 v6, v16, v6
	s_add_i32 s12, s40, s12
	v_lshrrev_b32_e32 v7, 2, v6
	v_lshlrev_b32_e32 v9, 1, v6
	v_and_b32_e32 v5, 0xc0, v5
	s_and_b32 s13, s12, -8
	v_and_b32_e32 v7, 4, v7
	v_and_b32_e32 v8, 3, v16
	v_and_b32_e32 v9, 0x1fffd8, v9
	v_sub_u32_e32 v4, v4, v5
	s_lshl_b32 s43, s27, 3
	s_sub_i32 s13, s40, s13
	v_or3_b32 v7, v8, v7, v9
	v_lshlrev_b32_e32 v8, 5, v15
	v_ashrrev_i16_sdwa v4, v205, sext(v4) dst_sel:DWORD dst_unused:UNUSED_PAD src0_sel:DWORD src1_sel:BYTE_0
	s_add_i32 s28, s43, s13
	s_ashr_i32 s12, s12, 3
	s_ashr_i32 s15, s14, 6
	v_and_b32_e32 v8, 32, v8
	v_bfe_i32 v17, v4, 0, 16
	s_sub_i32 s34, 15, s12
	s_ashr_i32 s29, s28, 31
	s_ashr_i32 s16, s14, 8
	s_lshl_b32 s42, s15, 10
	v_add_lshl_u32 v4, v8, v17, 1
	s_lshl_b64 s[12:13], s[28:29], 19
	s_lshl_b64 s[18:19], s[34:35], 19
	v_lshl_add_u32 v134, v7, 11, v4
	v_lshl_add_u32 v136, v6, 11, v4
	v_and_b32_e32 v4, 0x1fffd8, v156
	s_lshr_b32 s85, s40, 3
	s_add_i32 s85, s85, s40
	s_and_b32 s85, s85, 3
	s_lshl_b32 s85, s85, 8
	s_add_i32 s84, s85, 0x100
	s_add_u32 s36, s10, s18
	v_or3_b32 v4, v155, v4, v154
	v_lshlrev_b32_e32 v5, 1, v132
	s_addc_u32 s37, s11, s19
	s_add_u32 s36, s36, s85
	s_addc_u32 s37, s37, 0
	s_add_i32 s29, s42, 0
	v_lshl_add_u32 v138, v4, 11, v5
	s_add_i32 m0, s29, 0x10000
	v_lshl_add_u32 v140, v133, 11, v5
	global_load_lds_dwordx4 v138, s[36:37]
	s_add_i32 m0, s29, 0x12000
	s_add_u32 s18, s36, 0x10000
	global_load_lds_dwordx4 v134, s[36:37]
	s_addc_u32 s19, s37, 0
	s_add_i32 m0, s29, 0x14000
	v_mov_b32_e32 v139, v2
	global_load_lds_dwordx4 v138, s[18:19]
	s_add_i32 m0, s29, 0x16000
	s_add_u32 s30, s6, s12
	s_addc_u32 s31, s7, s13
	s_add_u32 s30, s30, s85
	s_addc_u32 s31, s31, 0
	s_add_i32 s54, s29, 0x2000
	global_load_lds_dwordx4 v134, s[18:19]
	s_mov_b32 m0, s29
	s_add_u32 s12, s30, 0x40000
	global_load_lds_dwordx4 v140, s[30:31]
	s_mov_b32 m0, s54
	s_addc_u32 s13, s31, 0
	s_add_i32 s55, s29, 0x4000
	global_load_lds_dwordx4 v136, s[30:31]
	s_mov_b32 m0, s55
	s_add_i32 s62, s29, 0x6000
	global_load_lds_dwordx4 v140, s[12:13]
	s_mov_b32 m0, s62
	v_mov_b32_e32 v135, v2
	global_load_lds_dwordx4 v136, s[12:13]
	v_mov_b32_e32 v141, v2
	v_mov_b32_e32 v137, v2
	s_cmp_eq_u32 s16, 1
	v_lshl_add_u64 v[10:11], s[36:37], 0, v[138:139]
	v_lshl_add_u64 v[8:9], s[36:37], 0, v[134:135]
	v_lshl_add_u64 v[4:5], s[30:31], 0, v[140:141]
	s_cselect_b64 s[12:13], -1, 0
	s_cmp_lg_u32 s16, 1
	v_lshl_add_u64 v[6:7], s[30:31], 0, v[136:137]
	s_cbranch_scc1 .LBB0_1374
	s_barrier
.LBB0_1374:
	v_lshlrev_b32_e32 v18, 1, v3
	v_lshlrev_b32_e32 v19, 2, v153
	s_and_b32 s17, s15, 3
	v_lshl_or_b32 v18, v153, 6, v18
	s_lshl_b32 s15, s16, 13
	v_and_b32_e32 v20, 32, v19
	s_add_i32 m0, s29, 0x18000
	v_lshl_add_u64 v[10:11], v[10:11], 0, s[52:53]
	v_bitop3_b32 v21, v18, s15, v20 bitop3:0xde
	s_lshl_b32 s15, s17, 12
	s_waitcnt vmcnt(2)
	s_barrier
	global_load_lds_dwordx4 v[10:11], off
	v_lshl_add_u64 v[8:9], v[8:9], 0, s[52:53]
	s_add_i32 m0, s29, 0x1a000
	s_add_i32 s63, s29, 0x8000
	s_add_i32 s64, s29, 0xa000
	global_load_lds_dwordx4 v[8:9], off
	v_lshl_add_u64 v[4:5], v[4:5], 0, s[52:53]
	s_mov_b32 m0, s63
	s_add_u32 s18, s36, 0x10080
	global_load_lds_dwordx4 v[4:5], off
	v_lshl_add_u64 v[4:5], v[6:7], 0, s[52:53]
	s_mov_b32 m0, s64
	s_addc_u32 s19, s37, 0
	global_load_lds_dwordx4 v[4:5], off
	s_add_i32 m0, s29, 0x1c000
	v_lshl_add_u64 v[4:5], s[18:19], 0, v[138:139]
	global_load_lds_dwordx4 v[4:5], off
	v_lshl_add_u64 v[4:5], s[18:19], 0, v[134:135]
	s_add_i32 m0, s29, 0x1e000
	s_cmpk_lt_u32 s14, 0x100
	global_load_lds_dwordx4 v[4:5], off
	v_cmp_lt_u32_e32 vcc, 7, v153
	v_bitop3_b32 v158, s15, v18, v20 bitop3:0xf6
	s_cselect_b64 s[14:15], -1, 0
	s_lshl_b32 s17, s17, 6
	v_cndmask_b32_e64 v4, 0, 32, vcc
	v_or3_b32 v162, s17, v4, v3
	v_lshlrev_b32_e32 v4, 14, v12
	v_and_b32_e32 v4, 0xffff8000, v4
	v_lshl_add_u32 v4, v13, 11, v4
	v_and_b32_e32 v5, 1, v12
	v_lshl_or_b32 v4, v5, 6, v4
	v_lshl_add_u32 v142, v14, 1, v4
	v_lshlrev_b32_e32 v4, 14, v15
	v_lshl_or_b32 v157, s16, 6, v153
	s_lshl_b32 s16, s16, 8
	v_and_b32_e32 v4, 0xffff8000, v4
	s_waitcnt vmcnt(6)
	s_add_i32 s16, s16, 0
	v_lshl_add_u32 v4, v16, 11, v4
	v_and_b32_e32 v5, 1, v15
	s_add_i32 s16, s16, 0x20000
	v_lshl_or_b32 v4, v5, 6, v4
	s_mov_b32 s65, 0
	v_cndmask_b32_e64 v159, 0, -8, vcc
	v_cndmask_b32_e64 v160, 8, 0, vcc
	v_add_u32_e32 v161, s16, v19
	v_mov_b32_e32 v143, v2
	v_lshl_add_u32 v144, v17, 1, v4
	v_mov_b32_e32 v145, v2
	v_add_u32_e32 v163, 0, v21
	s_barrier
	s_sub_u32 s36, s36, s85
	s_subb_u32 s37, s37, 0
	s_sub_u32 s30, s30, s85
	s_subb_u32 s31, s31, 0
	s_branch .LBB0_1377

;     DI bool next(int i, Unit& u) const { const int L = i * 32 + rank; if (L >= ppg * nN) return false; u.pm = ppg * grp + (L % ppg); const int p0 = L / ppg, p1 = p0 + rot; u.pn = rev ? nN - 1 - p0 : (p1 >= nN ? p1 - nN : p1); return true; }
; #define PG8_STAGE(bufoff, gbase, voff) do { _Pragma("unroll") for (int _i = 0; _i < 2; ++_i) \
;         __builtin_amdgcn_global_load_lds((const unsigned*)((const char*)(gbase) + (voff)[_i]), (PG8_LAS unsigned*)(lds + (bufoff) + ldsw + _i * 8192), 16, 0, 0); } while (0)
; #define PG8_LDA(dst, b, h) do { _Pragma("unroll") for (int m = 0; m < 4; ++m) _Pragma("unroll") for (int k = 0; k < 2; ++k) dst[m][k] = *(const PG8_LAS bf16x8*)(lds + PG8_SA(b, h) + aoff + m * 2048 + k * 1024); } while (0)
; #define PG8_LDB(dst, b, h) do { _Pragma("unroll") for (int n = 0; n < 2; ++n) _Pragma("unroll") for (int k = 0; k < 2; ++k) dst[n][k] = *(const PG8_LAS bf16x8*)(lds + PG8_SB(b, h) + boff + n * 2048 + k * 1024); } while (0)
; #define PG8_WAIT_V(n) asm volatile("s_waitcnt vmcnt(" #n ")" ::: "memory")
; #define PG8_WAIT_L(n) asm volatile("s_waitcnt lgkmcnt(" #n ")" ::: "memory")
; template <class Epi, class Sched, bool ALIGN_EPI = false, bool SP2 = false>
; __device__ __forceinline__ void gemm_phase(PG8_LAS unsigned char* lds, const Gemm g, const Sched& S, const Epi& E, const int tid) {
;     ...
;         const bool has_next = S.next(ui + 1, nxt);
;         const char* nA = has_next ? (const char*)g.A + (size_t)nxt.pm * tstep : cA; const char* nB = has_next ? (const char*)g.Bt + (size_t)nxt.pn * tstep : cB;
;         for (int t = 0; t < nt; t += 2) {
;             const bool last = (t == nt - 2);
;             const char* a1 = cA + (size_t)(t + 1) * kstep;
;             const char* a2 = last ? nA : cA + (size_t)(t + 2) * kstep; const char* b2 = last ? nB : cB + (size_t)(t + 2) * kstep;
;             const char* a3 = a2 + kstep; const char* b3 = b2 + kstep;
;             if (last && has_next) S.a_ready(nxt);
;             if constexpr (SP2) {
;             PG8_LDB(B0, 0, 0); PG8_LDB(B1, 0, 1); PG8_SCHED; PG8_LDA(At, 0, 0); PG8_STAGE(PG8_SA(1, 1), a1 + hstep, voffA);
;             PG8_WAIT_V(8); PG8_WAIT_L(0); PG8_BAR; PG8_MMA(0, 0, At, B0); PG8_MMA(0, 1, At, B1); PG8_BAR; PG8_SCHED;
;             PG8_LDA(At, 0, 1); PG8_STAGE(PG8_SB(0, 0), b2, voffB); PG8_STAGE(PG8_SB(0, 1), b2 + hstepB, voffB); PG8_STAGE(PG8_SA(0, 0), a2, voffA);
.LBB0_1379:
	s_ashr_i32 s17, s16, 31
	s_lshl_b64 s[20:21], s[16:17], 19
	s_add_u32 s20, s6, s20
	s_addc_u32 s21, s7, s21
	s_and_b64 s[24:25], s[22:23], exec
	s_cselect_b32 s17, s21, s31
	s_cselect_b32 s66, s20, s30
	s_add_u32 s66, s66, s85
	s_addc_u32 s17, s17, 0
	s_ashr_i32 s19, s18, 31
	s_lshl_b64 s[24:25], s[18:19], 19
	s_add_u32 s24, s10, s24
	s_addc_u32 s25, s11, s25
	s_and_b64 s[38:39], s[22:23], exec
	s_cselect_b32 s19, s25, s37
	s_cselect_b32 s67, s24, s36
	s_add_u32 s67, s67, s85
	s_addc_u32 s19, s19, 0
	s_add_u32 s30, s30, 0x40080
	s_addc_u32 s31, s31, 0
	s_mov_b32 s76, s36
	v_mov_b32_e32 v4, 0
	s_mov_b32 s78, s37
	s_mov_b32 s79, -2
	v_mov_b32_e32 v5, v4
	v_mov_b32_e32 v6, v4
	v_mov_b32_e32 v7, v4
	v_mov_b32_e32 v8, v4
	v_mov_b32_e32 v9, v4
	v_mov_b32_e32 v10, v4
	v_mov_b32_e32 v11, v4
	v_mov_b32_e32 v20, v4
	v_mov_b32_e32 v21, v4
	v_mov_b32_e32 v22, v4
	v_mov_b32_e32 v23, v4
	v_mov_b32_e32 v24, v4
	v_mov_b32_e32 v25, v4
	v_mov_b32_e32 v26, v4
	v_mov_b32_e32 v27, v4
	v_mov_b32_e32 v36, v4
	v_mov_b32_e32 v37, v4
	v_mov_b32_e32 v38, v4
	v_mov_b32_e32 v39, v4
	v_mov_b32_e32 v40, v4
	v_mov_b32_e32 v41, v4
	v_mov_b32_e32 v42, v4
	v_mov_b32_e32 v43, v4
	v_mov_b32_e32 v52, v4
	v_mov_b32_e32 v53, v4
	v_mov_b32_e32 v54, v4
	v_mov_b32_e32 v55, v4
	v_mov_b32_e32 v56, v4
	v_mov_b32_e32 v57, v4
	v_mov_b32_e32 v58, v4
	v_mov_b32_e32 v59, v4
	v_mov_b32_e32 v12, v4
	v_mov_b32_e32 v13, v4
	v_mov_b32_e32 v14, v4
	v_mov_b32_e32 v15, v4
	v_mov_b32_e32 v16, v4
	v_mov_b32_e32 v17, v4
	v_mov_b32_e32 v18, v4
	v_mov_b32_e32 v19, v4
	v_mov_b32_e32 v28, v4
	v_mov_b32_e32 v29, v4
	v_mov_b32_e32 v30, v4
	v_mov_b32_e32 v31, v4
	v_mov_b32_e32 v32, v4
	v_mov_b32_e32 v33, v4
	v_mov_b32_e32 v34, v4
	v_mov_b32_e32 v35, v4
	v_mov_b32_e32 v44, v4
	v_mov_b32_e32 v45, v4
	v_mov_b32_e32 v46, v4
	v_mov_b32_e32 v47, v4
	v_mov_b32_e32 v48, v4
	v_mov_b32_e32 v49, v4
	v_mov_b32_e32 v50, v4
	v_mov_b32_e32 v51, v4
	v_mov_b32_e32 v60, v4
	v_mov_b32_e32 v61, v4
	v_mov_b32_e32 v62, v4
	v_mov_b32_e32 v63, v4
	v_mov_b32_e32 v64, v4
	v_mov_b32_e32 v65, v4
	v_mov_b32_e32 v66, v4
	v_mov_b32_e32 v67, v4
	v_mov_b32_e32 v68, v4
	v_mov_b32_e32 v69, v4
	v_mov_b32_e32 v70, v4
	v_mov_b32_e32 v71, v4
	v_mov_b32_e32 v72, v4
	v_mov_b32_e32 v73, v4
	v_mov_b32_e32 v74, v4
	v_mov_b32_e32 v75, v4
	v_mov_b32_e32 v84, v4
	v_mov_b32_e32 v85, v4
	v_mov_b32_e32 v86, v4
	v_mov_b32_e32 v87, v4
	v_mov_b32_e32 v88, v4
	v_mov_b32_e32 v89, v4
	v_mov_b32_e32 v90, v4
	v_mov_b32_e32 v91, v4
	v_mov_b32_e32 v100, v4
	v_mov_b32_e32 v101, v4
	v_mov_b32_e32 v102, v4
	v_mov_b32_e32 v103, v4
	v_mov_b32_e32 v104, v4
	v_mov_b32_e32 v105, v4
	v_mov_b32_e32 v106, v4
	v_mov_b32_e32 v107, v4
	v_mov_b32_e32 v116, v4
	v_mov_b32_e32 v117, v4
	v_mov_b32_e32 v118, v4
	v_mov_b32_e32 v119, v4
	v_mov_b32_e32 v120, v4
	v_mov_b32_e32 v121, v4
	v_mov_b32_e32 v122, v4
	v_mov_b32_e32 v123, v4
	v_mov_b32_e32 v76, v4
	v_mov_b32_e32 v77, v4
	v_mov_b32_e32 v78, v4
	v_mov_b32_e32 v79, v4
	v_mov_b32_e32 v80, v4
	v_mov_b32_e32 v81, v4
	v_mov_b32_e32 v82, v4
	v_mov_b32_e32 v83, v4
	v_mov_b32_e32 v92, v4
	v_mov_b32_e32 v93, v4
	v_mov_b32_e32 v94, v4
	v_mov_b32_e32 v95, v4
	v_mov_b32_e32 v96, v4
	v_mov_b32_e32 v97, v4
	v_mov_b32_e32 v98, v4
	v_mov_b32_e32 v99, v4
	v_mov_b32_e32 v108, v4
	v_mov_b32_e32 v109, v4
	v_mov_b32_e32 v110, v4
	v_mov_b32_e32 v111, v4
	v_mov_b32_e32 v112, v4
	v_mov_b32_e32 v113, v4
	v_mov_b32_e32 v114, v4
	v_mov_b32_e32 v115, v4
	v_mov_b32_e32 v124, v4
	v_mov_b32_e32 v125, v4
	v_mov_b32_e32 v126, v4
	v_mov_b32_e32 v127, v4
	v_mov_b32_e32 v128, v4
	v_mov_b32_e32 v129, v4
	v_mov_b32_e32 v130, v4
	v_mov_b32_e32 v131, v4
.LBB0_1380:
	s_lshl_b32 s98, s79, 7
	s_add_i32 s98, s98, s84
	s_add_i32 s99, s98, 0x100
	s_and_b32 s98, s98, 0x700
	s_and_b32 s99, s99, 0x700
	s_add_u32 s100, s30, s98
	s_addc_u32 s101, s31, 0
	s_add_u32 s36, s30, 0xfffbff80
	s_addc_u32 s37, s31, -1
	s_add_u32 s36, s36, s99
	s_addc_u32 s37, s37, 0
	s_add_u32 s92, s76, s99
	s_addc_u32 s93, s78, 0
	s_add_i32 s80, 0, 0x10000
	s_cmp_eq_u32 s79, 12
	s_cselect_b32 s39, s17, s37
	s_cselect_b32 s38, s66, s36
	v_add_u32_e32 v150, s80, v158
	s_cselect_b32 s37, s19, s93
	s_cselect_b32 s36, s67, s92
	s_add_i32 s82, 0, 0x14000
	ds_read_b128 v[146:149], v150
	ds_read_b128 v[164:167], v150 offset:1024
	ds_read_b128 v[170:173], v150 offset:2048
	ds_read_b128 v[174:177], v150 offset:3072
	v_add_u32_e32 v150, s82, v158
	ds_read_b128 v[178:181], v150
	ds_read_b128 v[182:185], v150 offset:1024
	ds_read_b128 v[186:189], v150 offset:2048
	ds_read_b128 v[190:193], v150 offset:3072
	v_lshl_add_u64 v[150:151], s[100:101], 0, v[142:143]
	s_add_i32 m0, s29, 0xc000
	ds_read_b128 v[194:197], v163
	ds_read_b128 v[198:201], v163 offset:1024
	ds_read_b128 v[212:215], v163 offset:2048
	ds_read_b128 v[216:219], v163 offset:3072
	ds_read_b128 v[220:223], v163 offset:4096
	ds_read_b128 v[224:227], v163 offset:5120
	ds_read_b128 v[228:231], v163 offset:6144
	ds_read_b128 v[232:235], v163 offset:7168
	global_load_lds_dwordx4 v[150:151], off
	v_lshl_add_u64 v[150:151], s[100:101], 0, v[144:145]
	s_add_i32 m0, s29, 0xe000
	s_nop 0
	global_load_lds_dwordx4 v[150:151], off
	s_waitcnt vmcnt(8)
	s_waitcnt lgkmcnt(0)
	s_barrier
; #define PG8_STAGE(bufoff, gbase, voff) do { _Pragma("unroll") for (int _i = 0; _i < 2; ++_i) \
;         __builtin_amdgcn_global_load_lds((const unsigned*)((const char*)(gbase) + (voff)[_i]), (PG8_LAS unsigned*)(lds + (bufoff) + ldsw + _i * 8192), 16, 0, 0); } while (0)
; #define PG8_LDA(dst, b, h) do { _Pragma("unroll") for (int m = 0; m < 4; ++m) _Pragma("unroll") for (int k = 0; k < 2; ++k) dst[m][k] = *(const PG8_LAS bf16x8*)(lds + PG8_SA(b, h) + aoff + m * 2048 + k * 1024); } while (0)
; #define PG8_LDB(dst, b, h) do { _Pragma("unroll") for (int n = 0; n < 2; ++n) _Pragma("unroll") for (int k = 0; k < 2; ++k) dst[n][k] = *(const PG8_LAS bf16x8*)(lds + PG8_SB(b, h) + boff + n * 2048 + k * 1024); } while (0)
; #define PG8_MMA(ai, bj, At, Bt) do { __builtin_amdgcn_s_setprio(1); _Pragma("unroll") for (int m = 0; m < 4; ++m) _Pragma("unroll") for (int n = 0; n < 2; ++n) _Pragma("unroll") for (int k = 0; k < 2; ++k) \
;         acc[ai][bj][m][n] = __builtin_amdgcn_mfma_f32_16x16x32_bf16(Bt[n][k], At[m][k], acc[ai][bj][m][n], 0, 0, 0); __builtin_amdgcn_s_setprio(0); } while (0)
; #define PG8_WAIT_V(n) asm volatile("s_waitcnt vmcnt(" #n ")" ::: "memory")
; #define PG8_WAIT_L(n) asm volatile("s_waitcnt lgkmcnt(" #n ")" ::: "memory")
; #define PG8_BAR __builtin_amdgcn_s_barrier()
; #define PG8_SCHED __builtin_amdgcn_sched_barrier(0)
; template <class Epi, class Sched, bool ALIGN_EPI = false, bool SP2 = false>
; __device__ __forceinline__ void gemm_phase(PG8_LAS unsigned char* lds, const Gemm g, const Sched& S, const Epi& E, const int tid) {
;     ...
;             PG8_LDB(B0, 0, 0); PG8_LDB(B1, 0, 1); PG8_SCHED; PG8_LDA(At, 0, 0); PG8_STAGE(PG8_SA(1, 1), a1 + hstep, voffA);
;             PG8_WAIT_V(8); PG8_WAIT_L(0); PG8_BAR; PG8_MMA(0, 0, At, B0); PG8_MMA(0, 1, At, B1); PG8_BAR; PG8_SCHED;
;             PG8_LDA(At, 0, 1); PG8_STAGE(PG8_SB(0, 0), b2, voffB); PG8_STAGE(PG8_SB(0, 1), b2 + hstepB, voffB); PG8_STAGE(PG8_SA(0, 0), a2, voffA);
;             PG8_WAIT_V(8); PG8_WAIT_L(0); PG8_BAR; PG8_MMA(1, 0, At, B0); PG8_MMA(1, 1, At, B1); PG8_BAR; PG8_SCHED;
	s_setprio 1
	s_waitcnt lgkmcnt(0)
	v_mfma_f32_16x16x32_bf16 v[128:131], v[146:149], v[194:197], v[128:131]
	v_mfma_f32_16x16x32_bf16 v[124:127], v[170:173], v[194:197], v[124:127]
	v_mfma_f32_16x16x32_bf16 v[112:115], v[146:149], v[212:215], v[112:115]
	v_mfma_f32_16x16x32_bf16 v[108:111], v[170:173], v[212:215], v[108:111]
	v_mfma_f32_16x16x32_bf16 v[96:99], v[146:149], v[220:223], v[96:99]
	v_mfma_f32_16x16x32_bf16 v[92:95], v[170:173], v[220:223], v[92:95]
	v_mfma_f32_16x16x32_bf16 v[80:83], v[146:149], v[228:231], v[80:83]
	v_mfma_f32_16x16x32_bf16 v[76:79], v[170:173], v[228:231], v[76:79]
	v_mfma_f32_16x16x32_bf16 v[128:131], v[164:167], v[198:201], v[128:131]
	v_mfma_f32_16x16x32_bf16 v[124:127], v[174:177], v[198:201], v[124:127]
	v_mfma_f32_16x16x32_bf16 v[112:115], v[164:167], v[216:219], v[112:115]
	v_mfma_f32_16x16x32_bf16 v[108:111], v[174:177], v[216:219], v[108:111]
	v_mfma_f32_16x16x32_bf16 v[96:99], v[164:167], v[224:227], v[96:99]
	v_mfma_f32_16x16x32_bf16 v[92:95], v[174:177], v[224:227], v[92:95]
	v_mfma_f32_16x16x32_bf16 v[80:83], v[164:167], v[232:235], v[80:83]
	v_mfma_f32_16x16x32_bf16 v[76:79], v[174:177], v[232:235], v[76:79]
	s_setprio 0
	s_setprio 1
	v_mfma_f32_16x16x32_bf16 v[120:123], v[178:181], v[194:197], v[120:123]
	v_mfma_f32_16x16x32_bf16 v[116:119], v[186:189], v[194:197], v[116:119]
	v_mfma_f32_16x16x32_bf16 v[104:107], v[178:181], v[212:215], v[104:107]
	v_mfma_f32_16x16x32_bf16 v[100:103], v[186:189], v[212:215], v[100:103]
	v_mfma_f32_16x16x32_bf16 v[88:91], v[178:181], v[220:223], v[88:91]
	v_mfma_f32_16x16x32_bf16 v[84:87], v[186:189], v[220:223], v[84:87]
	v_mfma_f32_16x16x32_bf16 v[72:75], v[178:181], v[228:231], v[72:75]
	v_mfma_f32_16x16x32_bf16 v[68:71], v[186:189], v[228:231], v[68:71]
	v_mfma_f32_16x16x32_bf16 v[120:123], v[182:185], v[198:201], v[120:123]
	v_mfma_f32_16x16x32_bf16 v[116:119], v[190:193], v[198:201], v[116:119]
	v_mfma_f32_16x16x32_bf16 v[104:107], v[182:185], v[216:219], v[104:107]
	v_mfma_f32_16x16x32_bf16 v[100:103], v[190:193], v[216:219], v[100:103]
	v_mfma_f32_16x16x32_bf16 v[88:91], v[182:185], v[224:227], v[88:91]
	v_mfma_f32_16x16x32_bf16 v[84:87], v[190:193], v[224:227], v[84:87]
	v_mfma_f32_16x16x32_bf16 v[72:75], v[182:185], v[232:235], v[72:75]
	v_mfma_f32_16x16x32_bf16 v[68:71], v[190:193], v[232:235], v[68:71]
	s_setprio 0
	s_barrier
	s_add_i32 s80, s80, s42
	v_lshl_add_u64 v[150:151], s[36:37], 0, v[138:139]
	s_mov_b32 m0, s80
	ds_read_b128 v[194:197], v163 offset:16384
	ds_read_b128 v[198:201], v163 offset:17408
	ds_read_b128 v[212:215], v163 offset:18432
	ds_read_b128 v[216:219], v163 offset:19456
	ds_read_b128 v[220:223], v163 offset:20480
	ds_read_b128 v[224:227], v163 offset:21504
	ds_read_b128 v[228:231], v163 offset:22528
	ds_read_b128 v[232:235], v163 offset:23552
	global_load_lds_dwordx4 v[150:151], off
	s_add_i32 m0, s80, 0x2000
	s_add_u32 s80, s36, 0x10000
	v_lshl_add_u64 v[236:237], s[36:37], 0, v[134:135]
	s_addc_u32 s81, s37, 0
	s_add_i32 s82, s82, s42
	global_load_lds_dwordx4 v[236:237], off
	v_lshl_add_u64 v[238:239], s[80:81], 0, v[138:139]
	s_mov_b32 m0, s82
	v_lshl_add_u64 v[240:241], s[38:39], 0, v[136:137]
	global_load_lds_dwordx4 v[238:239], off
	v_lshl_add_u64 v[238:239], s[80:81], 0, v[134:135]
	s_add_i32 m0, s82, 0x2000
	s_nop 0
	global_load_lds_dwordx4 v[238:239], off
	v_lshl_add_u64 v[238:239], s[38:39], 0, v[140:141]
	s_mov_b32 m0, s29
	s_nop 0
	global_load_lds_dwordx4 v[238:239], off
	s_mov_b32 m0, s54
	s_nop 0
	global_load_lds_dwordx4 v[240:241], off
	s_waitcnt vmcnt(8)
	s_waitcnt lgkmcnt(0)
	s_barrier
	s_setprio 1
	s_waitcnt lgkmcnt(0)
	v_mfma_f32_16x16x32_bf16 v[64:67], v[146:149], v[194:197], v[64:67]
	v_mfma_f32_16x16x32_bf16 v[60:63], v[170:173], v[194:197], v[60:63]
	v_mfma_f32_16x16x32_bf16 v[48:51], v[146:149], v[212:215], v[48:51]
	v_mfma_f32_16x16x32_bf16 v[44:47], v[170:173], v[212:215], v[44:47]
	v_mfma_f32_16x16x32_bf16 v[32:35], v[146:149], v[220:223], v[32:35]
	v_mfma_f32_16x16x32_bf16 v[28:31], v[170:173], v[220:223], v[28:31]
	v_mfma_f32_16x16x32_bf16 v[16:19], v[146:149], v[228:231], v[16:19]
	v_mfma_f32_16x16x32_bf16 v[12:15], v[170:173], v[228:231], v[12:15]
	v_mfma_f32_16x16x32_bf16 v[64:67], v[164:167], v[198:201], v[64:67]
	v_mfma_f32_16x16x32_bf16 v[60:63], v[174:177], v[198:201], v[60:63]
	v_mfma_f32_16x16x32_bf16 v[48:51], v[164:167], v[216:219], v[48:51]
	v_mfma_f32_16x16x32_bf16 v[44:47], v[174:177], v[216:219], v[44:47]
	v_mfma_f32_16x16x32_bf16 v[32:35], v[164:167], v[224:227], v[32:35]
	v_mfma_f32_16x16x32_bf16 v[28:31], v[174:177], v[224:227], v[28:31]
	v_mfma_f32_16x16x32_bf16 v[16:19], v[164:167], v[232:235], v[16:19]
	v_mfma_f32_16x16x32_bf16 v[12:15], v[174:177], v[232:235], v[12:15]
	s_setprio 0
	s_setprio 1
	v_mfma_f32_16x16x32_bf16 v[56:59], v[178:181], v[194:197], v[56:59]
	v_mfma_f32_16x16x32_bf16 v[52:55], v[186:189], v[194:197], v[52:55]
	v_mfma_f32_16x16x32_bf16 v[40:43], v[178:181], v[212:215], v[40:43]
	v_mfma_f32_16x16x32_bf16 v[36:39], v[186:189], v[212:215], v[36:39]
	v_mfma_f32_16x16x32_bf16 v[24:27], v[178:181], v[220:223], v[24:27]
	v_mfma_f32_16x16x32_bf16 v[20:23], v[186:189], v[220:223], v[20:23]
	v_mfma_f32_16x16x32_bf16 v[8:11], v[178:181], v[228:231], v[8:11]
	v_mfma_f32_16x16x32_bf16 v[4:7], v[186:189], v[228:231], v[4:7]
	v_mfma_f32_16x16x32_bf16 v[56:59], v[182:185], v[198:201], v[56:59]
	v_mfma_f32_16x16x32_bf16 v[52:55], v[190:193], v[198:201], v[52:55]
	v_mfma_f32_16x16x32_bf16 v[40:43], v[182:185], v[216:219], v[40:43]
	v_mfma_f32_16x16x32_bf16 v[36:39], v[190:193], v[216:219], v[36:39]
	v_mfma_f32_16x16x32_bf16 v[24:27], v[182:185], v[224:227], v[24:27]
	v_mfma_f32_16x16x32_bf16 v[20:23], v[190:193], v[224:227], v[20:23]
	v_mfma_f32_16x16x32_bf16 v[8:11], v[182:185], v[232:235], v[8:11]
	v_mfma_f32_16x16x32_bf16 v[4:7], v[190:193], v[232:235], v[4:7]
	s_setprio 0
	s_barrier
; #define PG8_STAGE(bufoff, gbase, voff) do { _Pragma("unroll") for (int _i = 0; _i < 2; ++_i) \
;         __builtin_amdgcn_global_load_lds((const unsigned*)((const char*)(gbase) + (voff)[_i]), (PG8_LAS unsigned*)(lds + (bufoff) + ldsw + _i * 8192), 16, 0, 0); } while (0)
; #define PG8_LDA(dst, b, h) do { _Pragma("unroll") for (int m = 0; m < 4; ++m) _Pragma("unroll") for (int k = 0; k < 2; ++k) dst[m][k] = *(const PG8_LAS bf16x8*)(lds + PG8_SA(b, h) + aoff + m * 2048 + k * 1024); } while (0)
; #define PG8_LDB(dst, b, h) do { _Pragma("unroll") for (int n = 0; n < 2; ++n) _Pragma("unroll") for (int k = 0; k < 2; ++k) dst[n][k] = *(const PG8_LAS bf16x8*)(lds + PG8_SB(b, h) + boff + n * 2048 + k * 1024); } while (0)
; #define PG8_MMA(ai, bj, At, Bt) do { __builtin_amdgcn_s_setprio(1); _Pragma("unroll") for (int m = 0; m < 4; ++m) _Pragma("unroll") for (int n = 0; n < 2; ++n) _Pragma("unroll") for (int k = 0; k < 2; ++k) \
;         acc[ai][bj][m][n] = __builtin_amdgcn_mfma_f32_16x16x32_bf16(Bt[n][k], At[m][k], acc[ai][bj][m][n], 0, 0, 0); __builtin_amdgcn_s_setprio(0); } while (0)
; #define PG8_WAIT_V(n) asm volatile("s_waitcnt vmcnt(" #n ")" ::: "memory")
; #define PG8_WAIT_L(n) asm volatile("s_waitcnt lgkmcnt(" #n ")" ::: "memory")
; #define PG8_BAR __builtin_amdgcn_s_barrier()
; #define PG8_SCHED __builtin_amdgcn_sched_barrier(0)
; template <class Epi, class Sched, bool ALIGN_EPI = false, bool SP2 = false>
; __device__ __forceinline__ void gemm_phase(PG8_LAS unsigned char* lds, const Gemm g, const Sched& S, const Epi& E, const int tid) {
;     ...
;             PG8_LDB(B0, 1, 0); PG8_LDB(B1, 1, 1); PG8_SCHED; PG8_LDA(At, 1, 0); PG8_STAGE(PG8_SA(0, 1), a2 + hstep, voffA);
;             PG8_WAIT_V(8); PG8_WAIT_L(0); PG8_BAR; PG8_MMA(0, 0, At, B0); PG8_MMA(0, 1, At, B1); PG8_BAR; PG8_SCHED;
	s_add_i32 s80, 0, 0x18000
	s_add_i32 s81, 0, 0x1c000
	v_add_u32_e32 v174, s80, v158
	v_add_u32_e32 v190, s81, v158
	ds_read_b128 v[146:149], v174
	ds_read_b128 v[164:167], v174 offset:1024
	ds_read_b128 v[170:173], v174 offset:2048
	ds_read_b128 v[174:177], v174 offset:3072
	ds_read_b128 v[178:181], v190
	ds_read_b128 v[182:185], v190 offset:1024
	ds_read_b128 v[186:189], v190 offset:2048
	ds_read_b128 v[190:193], v190 offset:3072
	s_add_u32 s38, s38, 0x40000
	s_addc_u32 s39, s39, 0
	s_mov_b32 m0, s55
	v_lshl_add_u64 v[242:243], s[38:39], 0, v[140:141]
	ds_read_b128 v[194:197], v163 offset:32768
	ds_read_b128 v[198:201], v163 offset:33792
	ds_read_b128 v[212:215], v163 offset:34816
	ds_read_b128 v[216:219], v163 offset:35840
	ds_read_b128 v[220:223], v163 offset:36864
	ds_read_b128 v[224:227], v163 offset:37888
	ds_read_b128 v[228:231], v163 offset:38912
	ds_read_b128 v[232:235], v163 offset:39936
	global_load_lds_dwordx4 v[242:243], off
	v_lshl_add_u64 v[242:243], s[38:39], 0, v[136:137]
	s_mov_b32 m0, s62
	s_nop 0
	global_load_lds_dwordx4 v[242:243], off
	s_waitcnt vmcnt(8)
	s_waitcnt lgkmcnt(0)
	s_barrier
	s_setprio 1
	s_waitcnt lgkmcnt(0)
	v_mfma_f32_16x16x32_bf16 v[128:131], v[146:149], v[194:197], v[128:131]
	v_mfma_f32_16x16x32_bf16 v[124:127], v[170:173], v[194:197], v[124:127]
	v_mfma_f32_16x16x32_bf16 v[112:115], v[146:149], v[212:215], v[112:115]
	v_mfma_f32_16x16x32_bf16 v[108:111], v[170:173], v[212:215], v[108:111]
	v_mfma_f32_16x16x32_bf16 v[96:99], v[146:149], v[220:223], v[96:99]
	v_mfma_f32_16x16x32_bf16 v[92:95], v[170:173], v[220:223], v[92:95]
	v_mfma_f32_16x16x32_bf16 v[80:83], v[146:149], v[228:231], v[80:83]
	v_mfma_f32_16x16x32_bf16 v[76:79], v[170:173], v[228:231], v[76:79]
	v_mfma_f32_16x16x32_bf16 v[128:131], v[164:167], v[198:201], v[128:131]
	v_mfma_f32_16x16x32_bf16 v[124:127], v[174:177], v[198:201], v[124:127]
	v_mfma_f32_16x16x32_bf16 v[112:115], v[164:167], v[216:219], v[112:115]
	v_mfma_f32_16x16x32_bf16 v[108:111], v[174:177], v[216:219], v[108:111]
	v_mfma_f32_16x16x32_bf16 v[96:99], v[164:167], v[224:227], v[96:99]
	v_mfma_f32_16x16x32_bf16 v[92:95], v[174:177], v[224:227], v[92:95]
	v_mfma_f32_16x16x32_bf16 v[80:83], v[164:167], v[232:235], v[80:83]
	v_mfma_f32_16x16x32_bf16 v[76:79], v[174:177], v[232:235], v[76:79]
	s_setprio 0
	s_setprio 1
	v_mfma_f32_16x16x32_bf16 v[120:123], v[178:181], v[194:197], v[120:123]
	v_mfma_f32_16x16x32_bf16 v[116:119], v[186:189], v[194:197], v[116:119]
	v_mfma_f32_16x16x32_bf16 v[104:107], v[178:181], v[212:215], v[104:107]
	v_mfma_f32_16x16x32_bf16 v[100:103], v[186:189], v[212:215], v[100:103]
	v_mfma_f32_16x16x32_bf16 v[88:91], v[178:181], v[220:223], v[88:91]
	v_mfma_f32_16x16x32_bf16 v[84:87], v[186:189], v[220:223], v[84:87]
	v_mfma_f32_16x16x32_bf16 v[72:75], v[178:181], v[228:231], v[72:75]
	v_mfma_f32_16x16x32_bf16 v[68:71], v[186:189], v[228:231], v[68:71]
	v_mfma_f32_16x16x32_bf16 v[120:123], v[182:185], v[198:201], v[120:123]
	v_mfma_f32_16x16x32_bf16 v[116:119], v[190:193], v[198:201], v[116:119]
	v_mfma_f32_16x16x32_bf16 v[104:107], v[182:185], v[216:219], v[104:107]
	v_mfma_f32_16x16x32_bf16 v[100:103], v[190:193], v[216:219], v[100:103]
	v_mfma_f32_16x16x32_bf16 v[88:91], v[182:185], v[224:227], v[88:91]
	v_mfma_f32_16x16x32_bf16 v[84:87], v[190:193], v[224:227], v[84:87]
	v_mfma_f32_16x16x32_bf16 v[72:75], v[182:185], v[232:235], v[72:75]
	v_mfma_f32_16x16x32_bf16 v[68:71], v[190:193], v[232:235], v[68:71]
	s_setprio 0
	s_barrier
; #define PG8_STAGE(bufoff, gbase, voff) do { _Pragma("unroll") for (int _i = 0; _i < 2; ++_i) \
;         __builtin_amdgcn_global_load_lds((const unsigned*)((const char*)(gbase) + (voff)[_i]), (PG8_LAS unsigned*)(lds + (bufoff) + ldsw + _i * 8192), 16, 0, 0); } while (0)
; #define PG8_LDA(dst, b, h) do { _Pragma("unroll") for (int m = 0; m < 4; ++m) _Pragma("unroll") for (int k = 0; k < 2; ++k) dst[m][k] = *(const PG8_LAS bf16x8*)(lds + PG8_SA(b, h) + aoff + m * 2048 + k * 1024); } while (0)
; #define PG8_MMA(ai, bj, At, Bt) do { __builtin_amdgcn_s_setprio(1); _Pragma("unroll") for (int m = 0; m < 4; ++m) _Pragma("unroll") for (int n = 0; n < 2; ++n) _Pragma("unroll") for (int k = 0; k < 2; ++k) \
;         acc[ai][bj][m][n] = __builtin_amdgcn_mfma_f32_16x16x32_bf16(Bt[n][k], At[m][k], acc[ai][bj][m][n], 0, 0, 0); __builtin_amdgcn_s_setprio(0); } while (0)
; #define PG8_WAIT_V(n) asm volatile("s_waitcnt vmcnt(" #n ")" ::: "memory")
; #define PG8_WAIT_L(n) asm volatile("s_waitcnt lgkmcnt(" #n ")" ::: "memory")
; #define PG8_BAR __builtin_amdgcn_s_barrier()
; #define PG8_SCHED __builtin_amdgcn_sched_barrier(0)
; template <class Epi, class Sched, bool ALIGN_EPI = false, bool SP2 = false>
; __device__ __forceinline__ void gemm_phase(PG8_LAS unsigned char* lds, const Gemm g, const Sched& S, const Epi& E, const int tid) {
;     ...
;         for (int t = 0; t < nt; t += 2) {
;     ...
;             PG8_LDA(At, 1, 1); PG8_STAGE(PG8_SB(1, 0), b3, voffB); PG8_STAGE(PG8_SB(1, 1), b3 + hstepB, voffB); PG8_STAGE(PG8_SA(1, 0), a3, voffA);
;             PG8_WAIT_V(8); PG8_WAIT_L(0); PG8_BAR; PG8_MMA(1, 0, At, B0); PG8_MMA(1, 1, At, B1); PG8_BAR; PG8_SCHED;
	s_add_i32 s38, s80, s42
	v_lshl_add_u64 v[150:151], v[150:151], 0, s[52:53]
	s_mov_b32 m0, s38
	ds_read_b128 v[194:197], v163 offset:49152
	ds_read_b128 v[198:201], v163 offset:50176
	ds_read_b128 v[212:215], v163 offset:51200
	ds_read_b128 v[216:219], v163 offset:52224
	ds_read_b128 v[220:223], v163 offset:53248
	ds_read_b128 v[224:227], v163 offset:54272
	ds_read_b128 v[228:231], v163 offset:55296
	ds_read_b128 v[232:235], v163 offset:56320
	global_load_lds_dwordx4 v[150:151], off
	s_add_i32 m0, s38, 0x2000
	s_add_u32 s36, s36, 0x10080
	v_lshl_add_u64 v[150:151], v[236:237], 0, s[52:53]
	s_addc_u32 s37, s37, 0
	s_add_i32 s38, s81, s42
	global_load_lds_dwordx4 v[150:151], off
	v_lshl_add_u64 v[150:151], s[36:37], 0, v[138:139]
	s_mov_b32 m0, s38
	s_nop 0
	global_load_lds_dwordx4 v[150:151], off
	v_lshl_add_u64 v[150:151], s[36:37], 0, v[134:135]
	s_add_i32 m0, s38, 0x2000
	s_nop 0
	global_load_lds_dwordx4 v[150:151], off
	v_lshl_add_u64 v[150:151], v[238:239], 0, s[52:53]
	s_mov_b32 m0, s63
	s_nop 0
	global_load_lds_dwordx4 v[150:151], off
	v_lshl_add_u64 v[150:151], v[240:241], 0, s[52:53]
	s_mov_b32 m0, s64
	s_nop 0
	global_load_lds_dwordx4 v[150:151], off
	s_waitcnt vmcnt(8)
	s_waitcnt lgkmcnt(0)
	s_barrier
	s_setprio 1
	s_waitcnt lgkmcnt(0)
	v_mfma_f32_16x16x32_bf16 v[64:67], v[146:149], v[194:197], v[64:67]
	v_mfma_f32_16x16x32_bf16 v[60:63], v[170:173], v[194:197], v[60:63]
	v_mfma_f32_16x16x32_bf16 v[48:51], v[146:149], v[212:215], v[48:51]
	v_mfma_f32_16x16x32_bf16 v[44:47], v[170:173], v[212:215], v[44:47]
	v_mfma_f32_16x16x32_bf16 v[32:35], v[146:149], v[220:223], v[32:35]
	v_mfma_f32_16x16x32_bf16 v[28:31], v[170:173], v[220:223], v[28:31]
	v_mfma_f32_16x16x32_bf16 v[16:19], v[146:149], v[228:231], v[16:19]
	v_mfma_f32_16x16x32_bf16 v[12:15], v[170:173], v[228:231], v[12:15]
	v_mfma_f32_16x16x32_bf16 v[64:67], v[164:167], v[198:201], v[64:67]
	v_mfma_f32_16x16x32_bf16 v[60:63], v[174:177], v[198:201], v[60:63]
	v_mfma_f32_16x16x32_bf16 v[48:51], v[164:167], v[216:219], v[48:51]
	v_mfma_f32_16x16x32_bf16 v[44:47], v[174:177], v[216:219], v[44:47]
	v_mfma_f32_16x16x32_bf16 v[32:35], v[164:167], v[224:227], v[32:35]
	v_mfma_f32_16x16x32_bf16 v[28:31], v[174:177], v[224:227], v[28:31]
	v_mfma_f32_16x16x32_bf16 v[16:19], v[164:167], v[232:235], v[16:19]
	v_mfma_f32_16x16x32_bf16 v[12:15], v[174:177], v[232:235], v[12:15]
	s_setprio 0
	s_setprio 1
	v_mfma_f32_16x16x32_bf16 v[56:59], v[178:181], v[194:197], v[56:59]
	v_mfma_f32_16x16x32_bf16 v[52:55], v[186:189], v[194:197], v[52:55]
	v_mfma_f32_16x16x32_bf16 v[40:43], v[178:181], v[212:215], v[40:43]
	v_mfma_f32_16x16x32_bf16 v[36:39], v[186:189], v[212:215], v[36:39]
	v_mfma_f32_16x16x32_bf16 v[24:27], v[178:181], v[220:223], v[24:27]
	v_mfma_f32_16x16x32_bf16 v[20:23], v[186:189], v[220:223], v[20:23]
	v_mfma_f32_16x16x32_bf16 v[8:11], v[178:181], v[228:231], v[8:11]
	v_mfma_f32_16x16x32_bf16 v[4:7], v[186:189], v[228:231], v[4:7]
	v_mfma_f32_16x16x32_bf16 v[56:59], v[182:185], v[198:201], v[56:59]
	v_mfma_f32_16x16x32_bf16 v[52:55], v[190:193], v[198:201], v[52:55]
	v_mfma_f32_16x16x32_bf16 v[40:43], v[182:185], v[216:219], v[40:43]
	v_mfma_f32_16x16x32_bf16 v[36:39], v[190:193], v[216:219], v[36:39]
	v_mfma_f32_16x16x32_bf16 v[24:27], v[182:185], v[224:227], v[24:27]
	v_mfma_f32_16x16x32_bf16 v[20:23], v[190:193], v[224:227], v[20:23]
	v_mfma_f32_16x16x32_bf16 v[8:11], v[182:185], v[232:235], v[8:11]
	v_mfma_f32_16x16x32_bf16 v[4:7], v[190:193], v[232:235], v[4:7]
	s_setprio 0
	s_barrier
	s_add_i32 s79, s79, 2
	s_cmp_gt_u32 s79, 13
	s_cbranch_scc0 .LBB0_1380
	s_and_b64 vcc, exec, s[14:15]
	s_cbranch_vccz .LBB0_1383
	s_barrier
